# adds: phase W w_ple_gate transpose job loads (8 source + 8 gain) issued together with one wait
# speedup vs baseline: 1.0064x; 1.0009x over previous
; DI int opaque_bid() { int b = blockIdx.x; asm volatile("" : "+s"(b)); return b; }
; DI void transpose_job(const float* __restrict__ src, const float* __restrict__ gain, u16* __restrict__ dst, int K, int N, bool q8 = false) {
;     ...
;   for (int tile = opaque_bid(); tile < nk * nn; tile += gridDim.x) {
;     const int k0 = (tile / nn) << 6, n0 = (tile % nn) << 6;
; #pragma unroll
;     for (int i = 0; i < 8; ++i) {
;       int e = tid + i * NTHREADS, kk = e >> 6, c = e & 63;
;       float v = src[(size_t)(k0 + kk) * N + n0 + c];
;       if (gain) v *= gain[k0 + kk];
;       t[kk * 65 + c] = v;
;     }
;     __syncthreads();
; #pragma unroll
;     for (int i = 0; i < 8; ++i) {
;       int e = tid + i * NTHREADS, c = e >> 6, kk = e & 63;
;       if (q8) ((u8*)dst)[(size_t)(n0 + c) * K + k0 + kk] = (u8)(pk4_fp8(t[kk * 65 + c] * WQ_SCALE, 0.f, 0.f, 0.f) & 0xffu);
;       else dst[(size_t)(n0 + c) * K + k0 + kk] = (u16)(pk2(t[kk * 65 + c], 0.f) & 0xffffu);
;     }
;     __syncthreads();
; template <int CT>
; DI void phase_w() {
;     ...
;     transpose_job(p.w_ple_gate + (size_t)l * 1024 * 1024, p.norm_ple + l * 1024, WSU(WpgT) + (size_t)l * 1024 * 1024, 1024, 1024);
.LBB0_614:
	s_waitcnt lgkmcnt(0)
	s_barrier
	ds_read_b32 v8, v18
	s_sub_i32 s4, 0, s39
	s_add_i32 s4, s4, s53
	s_ashr_i32 s39, s38, 31
	v_lshl_add_u64 v[6:7], s[38:39], 1, v[4:5]
	s_waitcnt lgkmcnt(0)
	v_cvt_pk_bf16_f32 v33, v8, s0
	v_add_u32_e32 v8, s4, v10
	v_ashrrev_i32_e32 v9, 31, v8
	v_lshlrev_b64 v[8:9], 11, v[8:9]
	v_lshl_add_u64 v[8:9], v[6:7], 0, v[8:9]
	global_store_short v[8:9], v33, off
	ds_read_b32 v8, v19
	s_add_i32 s51, s51, s52
	s_add_i32 s53, s53, s54
	s_cmpk_lt_i32 s51, 0x100
	s_waitcnt lgkmcnt(0)
	v_cvt_pk_bf16_f32 v33, v8, s0
	v_add_u32_e32 v8, s4, v11
	v_ashrrev_i32_e32 v9, 31, v8
	v_lshlrev_b64 v[8:9], 11, v[8:9]
	v_lshl_add_u64 v[8:9], v[6:7], 0, v[8:9]
	global_store_short v[8:9], v33, off
	ds_read_b32 v8, v20
	s_waitcnt lgkmcnt(0)
	v_cvt_pk_bf16_f32 v33, v8, s0
	v_add_u32_e32 v8, s4, v12
	v_ashrrev_i32_e32 v9, 31, v8
	v_lshlrev_b64 v[8:9], 11, v[8:9]
	v_lshl_add_u64 v[8:9], v[6:7], 0, v[8:9]
	global_store_short v[8:9], v33, off
	ds_read_b32 v8, v21
	s_waitcnt lgkmcnt(0)
	v_cvt_pk_bf16_f32 v33, v8, s0
	v_add_u32_e32 v8, s4, v13
	v_ashrrev_i32_e32 v9, 31, v8
	v_lshlrev_b64 v[8:9], 11, v[8:9]
	v_lshl_add_u64 v[8:9], v[6:7], 0, v[8:9]
	global_store_short v[8:9], v33, off
	ds_read_b32 v8, v22
	s_waitcnt lgkmcnt(0)
	v_cvt_pk_bf16_f32 v33, v8, s0
	v_add_u32_e32 v8, s4, v14
	v_ashrrev_i32_e32 v9, 31, v8
	v_lshlrev_b64 v[8:9], 11, v[8:9]
	v_lshl_add_u64 v[8:9], v[6:7], 0, v[8:9]
	global_store_short v[8:9], v33, off
	ds_read_b32 v8, v23
	s_waitcnt lgkmcnt(0)
	v_cvt_pk_bf16_f32 v33, v8, s0
	v_add_u32_e32 v8, s4, v15
	v_ashrrev_i32_e32 v9, 31, v8
	v_lshlrev_b64 v[8:9], 11, v[8:9]
	v_lshl_add_u64 v[8:9], v[6:7], 0, v[8:9]
	global_store_short v[8:9], v33, off
	ds_read_b32 v8, v24
	s_waitcnt lgkmcnt(0)
	v_cvt_pk_bf16_f32 v33, v8, s0
	v_add_u32_e32 v8, s4, v16
	v_ashrrev_i32_e32 v9, 31, v8
	v_lshlrev_b64 v[8:9], 11, v[8:9]
	v_lshl_add_u64 v[8:9], v[6:7], 0, v[8:9]
	global_store_short v[8:9], v33, off
	ds_read_b32 v8, v25
	s_waitcnt lgkmcnt(0)
	v_cvt_pk_bf16_f32 v33, v8, s0
	v_add_u32_e32 v8, s4, v17
	v_ashrrev_i32_e32 v9, 31, v8
	v_lshlrev_b64 v[8:9], 11, v[8:9]
	v_lshl_add_u64 v[6:7], v[6:7], 0, v[8:9]
	global_store_short v[6:7], v33, off
	s_barrier
	s_cbranch_scc0 .LBB0_631
.LBB0_615:
	s_ashr_i32 s4, s51, 31
	s_lshr_b32 s4, s4, 28
	s_add_i32 s4, s51, s4
	s_ashr_i32 s4, s4, 4
	s_lshl_b32 s38, s4, 6
	s_lshl_b32 s39, s4, 10
	s_sub_i32 s4, s53, s39
	s_ashr_i32 s5, s4, 31
	v_lshl_add_u64 v[6:7], s[4:5], 2, v[2:3]
	v_add_u32_e32 v40, s38, v10
	v_ashrrev_i32_e32 v41, 31, v40
	v_lshlrev_b64 v[34:35], 12, v[40:41]
	v_lshl_add_u64 v[34:35], v[6:7], 0, v[34:35]
	global_load_dword v56, v[34:35], off
	v_add_u32_e32 v42, s38, v11
	v_ashrrev_i32_e32 v43, 31, v42
	v_lshlrev_b64 v[34:35], 12, v[42:43]
	v_lshl_add_u64 v[34:35], v[6:7], 0, v[34:35]
	global_load_dword v57, v[34:35], off
	v_add_u32_e32 v44, s38, v12
	v_ashrrev_i32_e32 v45, 31, v44
	v_lshlrev_b64 v[34:35], 12, v[44:45]
	v_lshl_add_u64 v[34:35], v[6:7], 0, v[34:35]
	global_load_dword v58, v[34:35], off
	v_add_u32_e32 v46, s38, v13
	v_ashrrev_i32_e32 v47, 31, v46
	v_lshlrev_b64 v[34:35], 12, v[46:47]
	v_lshl_add_u64 v[34:35], v[6:7], 0, v[34:35]
	global_load_dword v59, v[34:35], off
	v_add_u32_e32 v48, s38, v14
	v_ashrrev_i32_e32 v49, 31, v48
	v_lshlrev_b64 v[34:35], 12, v[48:49]
	v_lshl_add_u64 v[34:35], v[6:7], 0, v[34:35]
	global_load_dword v60, v[34:35], off
	v_add_u32_e32 v50, s38, v15
	v_ashrrev_i32_e32 v51, 31, v50
	v_lshlrev_b64 v[34:35], 12, v[50:51]
	v_lshl_add_u64 v[34:35], v[6:7], 0, v[34:35]
	global_load_dword v61, v[34:35], off
	v_add_u32_e32 v52, s38, v16
	v_ashrrev_i32_e32 v53, 31, v52
	v_lshlrev_b64 v[34:35], 12, v[52:53]
	v_lshl_add_u64 v[34:35], v[6:7], 0, v[34:35]
	global_load_dword v62, v[34:35], off
	v_add_u32_e32 v54, s38, v17
	v_ashrrev_i32_e32 v55, 31, v54
	v_lshlrev_b64 v[34:35], 12, v[54:55]
	v_lshl_add_u64 v[34:35], v[6:7], 0, v[34:35]
	global_load_dword v63, v[34:35], off
	s_andn2_b64 vcc, exec, s[26:27]
	s_cbranch_vccnz .Lw615_nogain
	v_lshl_add_u64 v[40:41], v[40:41], 2, s[30:31]
	global_load_dword v64, v[40:41], off
	v_lshl_add_u64 v[42:43], v[42:43], 2, s[30:31]
	global_load_dword v65, v[42:43], off
	v_lshl_add_u64 v[44:45], v[44:45], 2, s[30:31]
	global_load_dword v66, v[44:45], off
	v_lshl_add_u64 v[46:47], v[46:47], 2, s[30:31]
	global_load_dword v67, v[46:47], off
	v_lshl_add_u64 v[48:49], v[48:49], 2, s[30:31]
	global_load_dword v68, v[48:49], off
	v_lshl_add_u64 v[50:51], v[50:51], 2, s[30:31]
	global_load_dword v69, v[50:51], off
	v_lshl_add_u64 v[52:53], v[52:53], 2, s[30:31]
	global_load_dword v70, v[52:53], off
	v_lshl_add_u64 v[54:55], v[54:55], 2, s[30:31]
	global_load_dword v71, v[54:55], off
	s_waitcnt vmcnt(0)
	v_mul_f32_e32 v56, v56, v64
	v_mul_f32_e32 v57, v57, v65
	v_mul_f32_e32 v58, v58, v66
	v_mul_f32_e32 v59, v59, v67
	v_mul_f32_e32 v60, v60, v68
	v_mul_f32_e32 v61, v61, v69
	v_mul_f32_e32 v62, v62, v70
	v_mul_f32_e32 v63, v63, v71
.Lw615_nogain:
	s_waitcnt vmcnt(0)
	ds_write_b32 v26, v56
	ds_write_b32 v27, v57
	ds_write_b32 v28, v58
	ds_write_b32 v29, v59
	ds_write_b32 v30, v60
	ds_write_b32 v31, v61
	ds_write_b32 v32, v62
	ds_write_b32 v0, v63
	s_branch .LBB0_614

; #define LOAD_PARAMS() KParams kq_ = (KParams)__builtin_amdgcn_kernarg_segment_ptr(); asm volatile("" : "+s"(kq_)); const Params p = *kq_
; template <int CT>
; __global__ void __launch_bounds__(NTHREADS) mega_kernel(Params p) {
;     ...
; #pragma unroll 1
;   for (int ph = 0; ph < nph; ++ph) {
;     run_phase<CT>(ph);
;     if (ph + 1 < nph) {
;       LOAD_PARAMS();
;       xcd_barrier((unsigned*)(p.ws + WS<CT>::bar), x, nloc, nx, k);
;       ++k;
;     }
;   }
; }
.LBB0_726:
	s_endpgm
	s_nop 0
	s_nop 0
	s_nop 0
	s_nop 0
	s_nop 0
	s_nop 0
	s_nop 0
	s_nop 0
	s_nop 0
	s_nop 0
	s_nop 0
	s_nop 0
	s_nop 0
	s_nop 0
	s_nop 0
	s_nop 0
	s_nop 0
	s_nop 0
	s_nop 0
	s_nop 0
	s_nop 0
	s_nop 0
	s_nop 0
	s_nop 0
	s_nop 0
	s_nop 0
	s_nop 0
	s_nop 0
	s_nop 0
	s_nop 0
	s_nop 0
	s_nop 0
	s_nop 0
	s_nop 0
	s_nop 0
	s_nop 0
	s_nop 0
	s_nop 0
	s_nop 0
	s_nop 0
	s_nop 0
	s_nop 0
	s_nop 0
	s_nop 0
	s_nop 0
	s_nop 0
	s_nop 0
	s_nop 0
	s_nop 0
	s_nop 0
	s_nop 0
	s_nop 0
	s_nop 0
	s_nop 0
	s_nop 0
	s_endpgm
